# beta/alpha f32-MFMA GEMV: f32 weights staged once per workgroup in LDS in MFMA operand order (ds_read_b128 double-buffered) instead of every wave streaming them from global
# speedup vs baseline: 1.0054x; 1.0054x over previous
; __device__ __forceinline__ float bf2f(bfu h) { return __uint_as_float(((unsigned)h) << 16); }
; #define SHX(v, m) shx_((v), (m), lane)
; __device__ __forceinline__ int ptid_(int wave) { int l_; asm volatile("v_mbcnt_lo_u32_b32 %0, -1, 0\n\tv_mbcnt_hi_u32_b32 %0, -1, %0" : "=v"(l_)); return (wave << 6) | l_; }
; __device__ void ba_item(const Params& p, int L, int rp) {
;     ...
;   int tid = ptid_(p.tid); asm volatile("" : "+v"(tid));
;   const int wid = tid >> 6, lane = tid & 63;
;   f32x4 wr_[8][4];
;   _Pragma("unroll") for (int j = 0; j < 8; ++j) _Pragma("unroll") for (int e4 = 0; e4 < 4; ++e4)
;     wr_[j][e4] = *(const f32x4*)(wba + j * 1024 + lane * 16 + e4 * 4);
;   for (int bt = 0; bt < 8; ++bt) {
;     bf16x8 h0[2], h1[2]; f32x4 ps[2][4];
;     _Pragma("unroll") for (int u = 0; u < 2; ++u) {
;       const int row = rp * 128 + wid * 16 + bt * 2 + u;
;       const bfu* hr = hb + (long)row * 1024 + lane * 16;
;       h0[u] = *(const bf16x8*)hr; h1[u] = *(const bf16x8*)(hr + 8);
;       _Pragma("unroll") for (int i = 0; i < 4; ++i) ps[u][i] = *(const f32x4*)(rowss + (long)row * 16 + i * 4);
;     }
;     _Pragma("unroll") for (int u = 0; u < 2; ++u) {
;       const int row = rp * 128 + wid * 16 + bt * 2 + u;
;       float hf[16];
;       _Pragma("unroll") for (int e = 0; e < 8; ++e) { hf[e] = bf2f((bfu)h0[u][e]); hf[8 + e] = bf2f((bfu)h1[u][e]); }
;       float a[8];
;       _Pragma("unroll") for (int j = 0; j < 8; ++j) {
;         float s = 0.f;
;         _Pragma("unroll") for (int e4 = 0; e4 < 4; ++e4) _Pragma("unroll") for (int e = 0; e < 4; ++e) s += hf[e4 * 4 + e] * wr_[j][e4][e];
;         _Pragma("unroll") for (int o = 32; o >= 1; o >>= 1) s += SHX(s, o);
.LBB0_612:
	s_cmpk_gt_i32 s18, 0x6ff
	s_mov_b64 s[0:1], -1
	s_cbranch_scc0 .LBB0_628
	v_mbcnt_lo_u32_b32 v0, -1, 0
	v_mbcnt_hi_u32_b32 v0, -1, v0
	s_waitcnt vmcnt(0) lgkmcnt(0)
	s_barrier
	v_readlane_b32 s24, v254, 62
	v_readlane_b32 s25, v254, 63
	s_lshr_b32 s2, s33, 2
	s_add_i32 s2, s2, s20
	s_add_i32 s2, s2, 0xfffc8000
	v_and_b32_e32 v2, 15, v0
	v_lshrrev_b32_e32 v3, 4, v0
	v_or_b32_e32 v128, s33, v0
	v_lshlrev_b32_e32 v134, 4, v128
	global_load_dwordx4 v[136:139], v134, s[26:27]
	v_add_u32_e32 v134, 0x2000, v134
	global_load_dwordx4 v[140:143], v134, s[26:27]
	v_add_u32_e32 v134, 0x2000, v134
	global_load_dwordx4 v[144:147], v134, s[26:27]
	v_add_u32_e32 v134, 0x2000, v134
	global_load_dwordx4 v[148:151], v134, s[26:27]
	v_and_b32_e32 v129, 0xff, v128
	v_lshrrev_b32_e32 v133, 3, v129
	v_lshlrev_b32_e32 v133, 10, v133
	v_bfe_u32 v130, v128, 1, 2
	v_lshl_or_b32 v133, v130, 8, v133
	v_lshrrev_b32_e32 v130, 8, v128
	v_lshl_or_b32 v133, v130, 5, v133
	v_and_b32_e32 v130, 1, v128
	v_lshl_or_b32 v133, v130, 4, v133
	v_add_u32_e32 v128, s2, v2
	v_lshlrev_b32_e32 v128, 11, v128
	v_lshl_add_u32 v128, v3, 4, v128
	v_mov_b32_e32 v129, 0
	v_lshl_add_u64 v[4:5], s[80:81], 0, v[128:129]
	v_and_b32_e32 v122, 7, v2
	v_lshlrev_b32_e32 v132, 5, v122
	v_lshl_or_b32 v132, v3, 8, v132
	v_lshl_add_u32 v128, v3, 2, s2
	v_lshlrev_b32_e32 v128, 6, v128
	v_lshl_add_u64 v[120:121], s[24:25], 0, v[128:129]
	v_max_u32_e32 v128, 4, v122
	v_add_u32_e32 v128, s19, v128
	v_lshlrev_b32_e32 v128, 2, v128
	v_readlane_b32 s92, v254, 0
	v_readlane_b32 s93, v254, 1
	v_readlane_b32 s94, v254, 2
	v_readlane_b32 s95, v254, 3
	v_readlane_b32 s0, v252, 18
	v_readlane_b32 s1, v252, 19
	v_lshl_add_u32 v130, v3, 2, s2
	v_lshlrev_b32_e32 v130, 5, v130
	v_lshl_add_u32 v130, v122, 2, v130
	v_mov_b32_e32 v131, 0
	v_lshl_add_u64 v[124:125], s[0:1], 0, v[130:131]
	global_load_dword v126, v128, s[94:95]
	global_load_dword v127, v128, s[92:93]
	global_load_dwordx4 v[56:59], v[120:121], off offset:0
	global_load_dwordx4 v[60:63], v[120:121], off offset:16
	global_load_dwordx4 v[64:67], v[120:121], off offset:32
	global_load_dwordx4 v[68:71], v[120:121], off offset:48
	global_load_dwordx4 v[72:75], v[120:121], off offset:64
	global_load_dwordx4 v[76:79], v[120:121], off offset:80
	global_load_dwordx4 v[80:83], v[120:121], off offset:96
	global_load_dwordx4 v[84:87], v[120:121], off offset:112
	global_load_dwordx4 v[88:91], v[120:121], off offset:128
	global_load_dwordx4 v[92:95], v[120:121], off offset:144
	global_load_dwordx4 v[96:99], v[120:121], off offset:160
	global_load_dwordx4 v[100:103], v[120:121], off offset:176
	global_load_dwordx4 v[104:107], v[120:121], off offset:192
	global_load_dwordx4 v[108:111], v[120:121], off offset:208
	global_load_dwordx4 v[112:115], v[120:121], off offset:224
	global_load_dwordx4 v[116:119], v[120:121], off offset:240
	v_mov_b32_e32 v8, 0
	v_mov_b32_e32 v9, 0
	v_mov_b32_e32 v10, 0
	v_mov_b32_e32 v11, 0
	global_load_dwordx4 v[16:19], v[4:5], off
	global_load_dwordx4 v[20:23], v[4:5], off offset:64
	global_load_dwordx4 v[24:27], v[4:5], off offset:128
	global_load_dwordx4 v[28:31], v[4:5], off offset:192
	s_waitcnt vmcnt(22)
	ds_write_b128 v133, v[136:139]
	ds_write_b128 v133, v[140:143] offset:64
	ds_write_b128 v133, v[144:147] offset:128
	ds_write_b128 v133, v[148:151] offset:192
	s_waitcnt lgkmcnt(0)
	s_barrier
	ds_read_b128 v[32:35], v132
	ds_read_b128 v[36:39], v132 offset:16
	ds_read_b128 v[40:43], v132 offset:1024
	ds_read_b128 v[44:47], v132 offset:1040
	s_waitcnt vmcnt(3)
	v_lshlrev_b32_e32 v48, 16, v16
	v_and_b32_e32 v49, 0xffff0000, v16
	v_lshlrev_b32_e32 v50, 16, v17
	v_and_b32_e32 v51, 0xffff0000, v17
	v_lshlrev_b32_e32 v52, 16, v18
	v_and_b32_e32 v53, 0xffff0000, v18
	v_lshlrev_b32_e32 v54, 16, v19
	v_and_b32_e32 v55, 0xffff0000, v19
	s_waitcnt lgkmcnt(2)
	v_mfma_f32_16x16x4_f32 v[8:11], v48, v32, v[8:11]
	v_mfma_f32_16x16x4_f32 v[8:11], v49, v33, v[8:11]
	v_mfma_f32_16x16x4_f32 v[8:11], v50, v34, v[8:11]
	v_mfma_f32_16x16x4_f32 v[8:11], v51, v35, v[8:11]
	v_mfma_f32_16x16x4_f32 v[8:11], v52, v36, v[8:11]
	v_mfma_f32_16x16x4_f32 v[8:11], v53, v37, v[8:11]
	v_mfma_f32_16x16x4_f32 v[8:11], v54, v38, v[8:11]
	v_mfma_f32_16x16x4_f32 v[8:11], v55, v39, v[8:11]
	global_load_dwordx4 v[16:19], v[4:5], off offset:256
	ds_read_b128 v[32:35], v132 offset:2048
	ds_read_b128 v[36:39], v132 offset:2064
	s_waitcnt vmcnt(3)
	v_lshlrev_b32_e32 v48, 16, v20
	v_and_b32_e32 v49, 0xffff0000, v20
	v_lshlrev_b32_e32 v50, 16, v21
	v_and_b32_e32 v51, 0xffff0000, v21
	v_lshlrev_b32_e32 v52, 16, v22
	v_and_b32_e32 v53, 0xffff0000, v22
	v_lshlrev_b32_e32 v54, 16, v23
	v_and_b32_e32 v55, 0xffff0000, v23
	s_waitcnt lgkmcnt(2)
	v_mfma_f32_16x16x4_f32 v[8:11], v48, v40, v[8:11]
	v_mfma_f32_16x16x4_f32 v[8:11], v49, v41, v[8:11]
	v_mfma_f32_16x16x4_f32 v[8:11], v50, v42, v[8:11]
	v_mfma_f32_16x16x4_f32 v[8:11], v51, v43, v[8:11]
	v_mfma_f32_16x16x4_f32 v[8:11], v52, v44, v[8:11]
	v_mfma_f32_16x16x4_f32 v[8:11], v53, v45, v[8:11]
	v_mfma_f32_16x16x4_f32 v[8:11], v54, v46, v[8:11]
	v_mfma_f32_16x16x4_f32 v[8:11], v55, v47, v[8:11]
	global_load_dwordx4 v[20:23], v[4:5], off offset:320
	ds_read_b128 v[40:43], v132 offset:3072
	ds_read_b128 v[44:47], v132 offset:3088
	s_waitcnt vmcnt(3)
	v_lshlrev_b32_e32 v48, 16, v24
	v_and_b32_e32 v49, 0xffff0000, v24
	v_lshlrev_b32_e32 v50, 16, v25
	v_and_b32_e32 v51, 0xffff0000, v25
	v_lshlrev_b32_e32 v52, 16, v26
	v_and_b32_e32 v53, 0xffff0000, v26
	v_lshlrev_b32_e32 v54, 16, v27
	v_and_b32_e32 v55, 0xffff0000, v27
	s_waitcnt lgkmcnt(2)
; #define SHX(v, m) shx_((v), (m), lane)
; __device__ void ba_item(const Params& p, int L, int rp) {
;     ...
;       _Pragma("unroll") for (int j = 0; j < 8; ++j) {
;         float s = 0.f;
;         _Pragma("unroll") for (int e4 = 0; e4 < 4; ++e4) _Pragma("unroll") for (int e = 0; e < 4; ++e) s += hf[e4 * 4 + e] * wr_[j][e4][e];
;         _Pragma("unroll") for (int o = 32; o >= 1; o >>= 1) s += SHX(s, o);
	v_mfma_f32_16x16x4_f32 v[8:11], v48, v32, v[8:11]
	v_mfma_f32_16x16x4_f32 v[8:11], v49, v33, v[8:11]
	v_mfma_f32_16x16x4_f32 v[8:11], v50, v34, v[8:11]
	v_mfma_f32_16x16x4_f32 v[8:11], v51, v35, v[8:11]
	v_mfma_f32_16x16x4_f32 v[8:11], v52, v36, v[8:11]
	v_mfma_f32_16x16x4_f32 v[8:11], v53, v37, v[8:11]
	v_mfma_f32_16x16x4_f32 v[8:11], v54, v38, v[8:11]
	v_mfma_f32_16x16x4_f32 v[8:11], v55, v39, v[8:11]
	global_load_dwordx4 v[24:27], v[4:5], off offset:384
	ds_read_b128 v[32:35], v132 offset:4096
	ds_read_b128 v[36:39], v132 offset:4112
	s_waitcnt vmcnt(3)
	v_lshlrev_b32_e32 v48, 16, v28
	v_and_b32_e32 v49, 0xffff0000, v28
	v_lshlrev_b32_e32 v50, 16, v29
	v_and_b32_e32 v51, 0xffff0000, v29
	v_lshlrev_b32_e32 v52, 16, v30
	v_and_b32_e32 v53, 0xffff0000, v30
	v_lshlrev_b32_e32 v54, 16, v31
	v_and_b32_e32 v55, 0xffff0000, v31
	s_waitcnt lgkmcnt(2)
	v_mfma_f32_16x16x4_f32 v[8:11], v48, v40, v[8:11]
	v_mfma_f32_16x16x4_f32 v[8:11], v49, v41, v[8:11]
	v_mfma_f32_16x16x4_f32 v[8:11], v50, v42, v[8:11]
	v_mfma_f32_16x16x4_f32 v[8:11], v51, v43, v[8:11]
	v_mfma_f32_16x16x4_f32 v[8:11], v52, v44, v[8:11]
	v_mfma_f32_16x16x4_f32 v[8:11], v53, v45, v[8:11]
	v_mfma_f32_16x16x4_f32 v[8:11], v54, v46, v[8:11]
	v_mfma_f32_16x16x4_f32 v[8:11], v55, v47, v[8:11]
	global_load_dwordx4 v[28:31], v[4:5], off offset:448
	ds_read_b128 v[40:43], v132 offset:5120
	ds_read_b128 v[44:47], v132 offset:5136
	s_waitcnt vmcnt(3)
	v_lshlrev_b32_e32 v48, 16, v16
	v_and_b32_e32 v49, 0xffff0000, v16
	v_lshlrev_b32_e32 v50, 16, v17
	v_and_b32_e32 v51, 0xffff0000, v17
	v_lshlrev_b32_e32 v52, 16, v18
	v_and_b32_e32 v53, 0xffff0000, v18
	v_lshlrev_b32_e32 v54, 16, v19
	v_and_b32_e32 v55, 0xffff0000, v19
	s_waitcnt lgkmcnt(2)
	v_mfma_f32_16x16x4_f32 v[8:11], v48, v32, v[8:11]
	v_mfma_f32_16x16x4_f32 v[8:11], v49, v33, v[8:11]
	v_mfma_f32_16x16x4_f32 v[8:11], v50, v34, v[8:11]
	v_mfma_f32_16x16x4_f32 v[8:11], v51, v35, v[8:11]
	v_mfma_f32_16x16x4_f32 v[8:11], v52, v36, v[8:11]
	v_mfma_f32_16x16x4_f32 v[8:11], v53, v37, v[8:11]
	v_mfma_f32_16x16x4_f32 v[8:11], v54, v38, v[8:11]
	v_mfma_f32_16x16x4_f32 v[8:11], v55, v39, v[8:11]
	global_load_dwordx4 v[16:19], v[4:5], off offset:512
	ds_read_b128 v[32:35], v132 offset:6144
	ds_read_b128 v[36:39], v132 offset:6160
	s_waitcnt vmcnt(3)
	v_lshlrev_b32_e32 v48, 16, v20
	v_and_b32_e32 v49, 0xffff0000, v20
	v_lshlrev_b32_e32 v50, 16, v21
	v_and_b32_e32 v51, 0xffff0000, v21
	v_lshlrev_b32_e32 v52, 16, v22
	v_and_b32_e32 v53, 0xffff0000, v22
	v_lshlrev_b32_e32 v54, 16, v23
	v_and_b32_e32 v55, 0xffff0000, v23
	s_waitcnt lgkmcnt(2)
	v_mfma_f32_16x16x4_f32 v[8:11], v48, v40, v[8:11]
	v_mfma_f32_16x16x4_f32 v[8:11], v49, v41, v[8:11]
	v_mfma_f32_16x16x4_f32 v[8:11], v50, v42, v[8:11]
	v_mfma_f32_16x16x4_f32 v[8:11], v51, v43, v[8:11]
	v_mfma_f32_16x16x4_f32 v[8:11], v52, v44, v[8:11]
	v_mfma_f32_16x16x4_f32 v[8:11], v53, v45, v[8:11]
	v_mfma_f32_16x16x4_f32 v[8:11], v54, v46, v[8:11]
	v_mfma_f32_16x16x4_f32 v[8:11], v55, v47, v[8:11]
	global_load_dwordx4 v[20:23], v[4:5], off offset:576
	ds_read_b128 v[40:43], v132 offset:7168
	ds_read_b128 v[44:47], v132 offset:7184
	s_waitcnt vmcnt(3)
	v_lshlrev_b32_e32 v48, 16, v24
	v_and_b32_e32 v49, 0xffff0000, v24
	v_lshlrev_b32_e32 v50, 16, v25
	v_and_b32_e32 v51, 0xffff0000, v25
	v_lshlrev_b32_e32 v52, 16, v26
	v_and_b32_e32 v53, 0xffff0000, v26
	v_lshlrev_b32_e32 v54, 16, v27
	v_and_b32_e32 v55, 0xffff0000, v27
	s_waitcnt lgkmcnt(2)
	v_mfma_f32_16x16x4_f32 v[8:11], v48, v32, v[8:11]
	v_mfma_f32_16x16x4_f32 v[8:11], v49, v33, v[8:11]
	v_mfma_f32_16x16x4_f32 v[8:11], v50, v34, v[8:11]
	v_mfma_f32_16x16x4_f32 v[8:11], v51, v35, v[8:11]
	v_mfma_f32_16x16x4_f32 v[8:11], v52, v36, v[8:11]
	v_mfma_f32_16x16x4_f32 v[8:11], v53, v37, v[8:11]
	v_mfma_f32_16x16x4_f32 v[8:11], v54, v38, v[8:11]
	v_mfma_f32_16x16x4_f32 v[8:11], v55, v39, v[8:11]
	global_load_dwordx4 v[24:27], v[4:5], off offset:640
	ds_read_b128 v[32:35], v132 offset:8192
	ds_read_b128 v[36:39], v132 offset:8208
	s_waitcnt vmcnt(3)
	v_lshlrev_b32_e32 v48, 16, v28
	v_and_b32_e32 v49, 0xffff0000, v28
	v_lshlrev_b32_e32 v50, 16, v29
	v_and_b32_e32 v51, 0xffff0000, v29
	v_lshlrev_b32_e32 v52, 16, v30
	v_and_b32_e32 v53, 0xffff0000, v30
	v_lshlrev_b32_e32 v54, 16, v31
	v_and_b32_e32 v55, 0xffff0000, v31
	s_waitcnt lgkmcnt(2)
	v_mfma_f32_16x16x4_f32 v[8:11], v48, v40, v[8:11]
	v_mfma_f32_16x16x4_f32 v[8:11], v49, v41, v[8:11]
	v_mfma_f32_16x16x4_f32 v[8:11], v50, v42, v[8:11]
	v_mfma_f32_16x16x4_f32 v[8:11], v51, v43, v[8:11]
	v_mfma_f32_16x16x4_f32 v[8:11], v52, v44, v[8:11]
	v_mfma_f32_16x16x4_f32 v[8:11], v53, v45, v[8:11]
	v_mfma_f32_16x16x4_f32 v[8:11], v54, v46, v[8:11]
	v_mfma_f32_16x16x4_f32 v[8:11], v55, v47, v[8:11]
	global_load_dwordx4 v[28:31], v[4:5], off offset:704
	ds_read_b128 v[40:43], v132 offset:9216
	ds_read_b128 v[44:47], v132 offset:9232
	s_waitcnt vmcnt(3)
	v_lshlrev_b32_e32 v48, 16, v16
	v_and_b32_e32 v49, 0xffff0000, v16
	v_lshlrev_b32_e32 v50, 16, v17
	v_and_b32_e32 v51, 0xffff0000, v17
	v_lshlrev_b32_e32 v52, 16, v18
	v_and_b32_e32 v53, 0xffff0000, v18
	v_lshlrev_b32_e32 v54, 16, v19
	v_and_b32_e32 v55, 0xffff0000, v19
	s_waitcnt lgkmcnt(2)
	v_mfma_f32_16x16x4_f32 v[8:11], v48, v32, v[8:11]
	v_mfma_f32_16x16x4_f32 v[8:11], v49, v33, v[8:11]
	v_mfma_f32_16x16x4_f32 v[8:11], v50, v34, v[8:11]
	v_mfma_f32_16x16x4_f32 v[8:11], v51, v35, v[8:11]
	v_mfma_f32_16x16x4_f32 v[8:11], v52, v36, v[8:11]
	v_mfma_f32_16x16x4_f32 v[8:11], v53, v37, v[8:11]
	v_mfma_f32_16x16x4_f32 v[8:11], v54, v38, v[8:11]
	v_mfma_f32_16x16x4_f32 v[8:11], v55, v39, v[8:11]
	global_load_dwordx4 v[16:19], v[4:5], off offset:768
	ds_read_b128 v[32:35], v132 offset:10240
	ds_read_b128 v[36:39], v132 offset:10256
	s_waitcnt vmcnt(3)
; #define SHX(v, m) shx_((v), (m), lane)
; __device__ void ba_item(const Params& p, int L, int rp) {
;     ...
;       _Pragma("unroll") for (int j = 0; j < 8; ++j) {
;         float s = 0.f;
;         _Pragma("unroll") for (int e4 = 0; e4 < 4; ++e4) _Pragma("unroll") for (int e = 0; e < 4; ++e) s += hf[e4 * 4 + e] * wr_[j][e4][e];
;         _Pragma("unroll") for (int o = 32; o >= 1; o >>= 1) s += SHX(s, o);
	v_lshlrev_b32_e32 v48, 16, v20
	v_and_b32_e32 v49, 0xffff0000, v20
	v_lshlrev_b32_e32 v50, 16, v21
	v_and_b32_e32 v51, 0xffff0000, v21
	v_lshlrev_b32_e32 v52, 16, v22
	v_and_b32_e32 v53, 0xffff0000, v22
	v_lshlrev_b32_e32 v54, 16, v23
	v_and_b32_e32 v55, 0xffff0000, v23
	s_waitcnt lgkmcnt(2)
	v_mfma_f32_16x16x4_f32 v[8:11], v48, v40, v[8:11]
	v_mfma_f32_16x16x4_f32 v[8:11], v49, v41, v[8:11]
	v_mfma_f32_16x16x4_f32 v[8:11], v50, v42, v[8:11]
	v_mfma_f32_16x16x4_f32 v[8:11], v51, v43, v[8:11]
	v_mfma_f32_16x16x4_f32 v[8:11], v52, v44, v[8:11]
	v_mfma_f32_16x16x4_f32 v[8:11], v53, v45, v[8:11]
	v_mfma_f32_16x16x4_f32 v[8:11], v54, v46, v[8:11]
	v_mfma_f32_16x16x4_f32 v[8:11], v55, v47, v[8:11]
	global_load_dwordx4 v[20:23], v[4:5], off offset:832
	ds_read_b128 v[40:43], v132 offset:11264
	ds_read_b128 v[44:47], v132 offset:11280
	s_waitcnt vmcnt(3)
	v_lshlrev_b32_e32 v48, 16, v24
	v_and_b32_e32 v49, 0xffff0000, v24
	v_lshlrev_b32_e32 v50, 16, v25
	v_and_b32_e32 v51, 0xffff0000, v25
	v_lshlrev_b32_e32 v52, 16, v26
	v_and_b32_e32 v53, 0xffff0000, v26
	v_lshlrev_b32_e32 v54, 16, v27
	v_and_b32_e32 v55, 0xffff0000, v27
	s_waitcnt lgkmcnt(2)
	v_mfma_f32_16x16x4_f32 v[8:11], v48, v32, v[8:11]
	v_mfma_f32_16x16x4_f32 v[8:11], v49, v33, v[8:11]
	v_mfma_f32_16x16x4_f32 v[8:11], v50, v34, v[8:11]
	v_mfma_f32_16x16x4_f32 v[8:11], v51, v35, v[8:11]
	v_mfma_f32_16x16x4_f32 v[8:11], v52, v36, v[8:11]
	v_mfma_f32_16x16x4_f32 v[8:11], v53, v37, v[8:11]
	v_mfma_f32_16x16x4_f32 v[8:11], v54, v38, v[8:11]
	v_mfma_f32_16x16x4_f32 v[8:11], v55, v39, v[8:11]
	global_load_dwordx4 v[24:27], v[4:5], off offset:896
	ds_read_b128 v[32:35], v132 offset:12288
	ds_read_b128 v[36:39], v132 offset:12304
	s_waitcnt vmcnt(3)
	v_lshlrev_b32_e32 v48, 16, v28
	v_and_b32_e32 v49, 0xffff0000, v28
	v_lshlrev_b32_e32 v50, 16, v29
	v_and_b32_e32 v51, 0xffff0000, v29
	v_lshlrev_b32_e32 v52, 16, v30
	v_and_b32_e32 v53, 0xffff0000, v30
	v_lshlrev_b32_e32 v54, 16, v31
	v_and_b32_e32 v55, 0xffff0000, v31
	s_waitcnt lgkmcnt(2)
	v_mfma_f32_16x16x4_f32 v[8:11], v48, v40, v[8:11]
	v_mfma_f32_16x16x4_f32 v[8:11], v49, v41, v[8:11]
	v_mfma_f32_16x16x4_f32 v[8:11], v50, v42, v[8:11]
	v_mfma_f32_16x16x4_f32 v[8:11], v51, v43, v[8:11]
	v_mfma_f32_16x16x4_f32 v[8:11], v52, v44, v[8:11]
	v_mfma_f32_16x16x4_f32 v[8:11], v53, v45, v[8:11]
	v_mfma_f32_16x16x4_f32 v[8:11], v54, v46, v[8:11]
	v_mfma_f32_16x16x4_f32 v[8:11], v55, v47, v[8:11]
	global_load_dwordx4 v[28:31], v[4:5], off offset:960
	ds_read_b128 v[40:43], v132 offset:13312
	ds_read_b128 v[44:47], v132 offset:13328
	s_waitcnt vmcnt(3)
	v_lshlrev_b32_e32 v48, 16, v16
	v_and_b32_e32 v49, 0xffff0000, v16
	v_lshlrev_b32_e32 v50, 16, v17
	v_and_b32_e32 v51, 0xffff0000, v17
	v_lshlrev_b32_e32 v52, 16, v18
	v_and_b32_e32 v53, 0xffff0000, v18
	v_lshlrev_b32_e32 v54, 16, v19
	v_and_b32_e32 v55, 0xffff0000, v19
	s_waitcnt lgkmcnt(2)
	v_mfma_f32_16x16x4_f32 v[8:11], v48, v32, v[8:11]
	v_mfma_f32_16x16x4_f32 v[8:11], v49, v33, v[8:11]
	v_mfma_f32_16x16x4_f32 v[8:11], v50, v34, v[8:11]
	v_mfma_f32_16x16x4_f32 v[8:11], v51, v35, v[8:11]
	v_mfma_f32_16x16x4_f32 v[8:11], v52, v36, v[8:11]
	v_mfma_f32_16x16x4_f32 v[8:11], v53, v37, v[8:11]
	v_mfma_f32_16x16x4_f32 v[8:11], v54, v38, v[8:11]
	v_mfma_f32_16x16x4_f32 v[8:11], v55, v39, v[8:11]
	global_load_dwordx4 v[16:19], v[4:5], off offset:1024
	ds_read_b128 v[32:35], v132 offset:14336
	ds_read_b128 v[36:39], v132 offset:14352
	s_waitcnt vmcnt(3)
	v_lshlrev_b32_e32 v48, 16, v20
	v_and_b32_e32 v49, 0xffff0000, v20
	v_lshlrev_b32_e32 v50, 16, v21
	v_and_b32_e32 v51, 0xffff0000, v21
	v_lshlrev_b32_e32 v52, 16, v22
	v_and_b32_e32 v53, 0xffff0000, v22
	v_lshlrev_b32_e32 v54, 16, v23
	v_and_b32_e32 v55, 0xffff0000, v23
	s_waitcnt lgkmcnt(2)
	v_mfma_f32_16x16x4_f32 v[8:11], v48, v40, v[8:11]
	v_mfma_f32_16x16x4_f32 v[8:11], v49, v41, v[8:11]
	v_mfma_f32_16x16x4_f32 v[8:11], v50, v42, v[8:11]
	v_mfma_f32_16x16x4_f32 v[8:11], v51, v43, v[8:11]
	v_mfma_f32_16x16x4_f32 v[8:11], v52, v44, v[8:11]
	v_mfma_f32_16x16x4_f32 v[8:11], v53, v45, v[8:11]
	v_mfma_f32_16x16x4_f32 v[8:11], v54, v46, v[8:11]
	v_mfma_f32_16x16x4_f32 v[8:11], v55, v47, v[8:11]
	global_load_dwordx4 v[20:23], v[4:5], off offset:1088
	ds_read_b128 v[40:43], v132 offset:15360
	ds_read_b128 v[44:47], v132 offset:15376
	s_waitcnt vmcnt(3)
	v_lshlrev_b32_e32 v48, 16, v24
	v_and_b32_e32 v49, 0xffff0000, v24
	v_lshlrev_b32_e32 v50, 16, v25
	v_and_b32_e32 v51, 0xffff0000, v25
	v_lshlrev_b32_e32 v52, 16, v26
	v_and_b32_e32 v53, 0xffff0000, v26
	v_lshlrev_b32_e32 v54, 16, v27
	v_and_b32_e32 v55, 0xffff0000, v27
	s_waitcnt lgkmcnt(2)
	v_mfma_f32_16x16x4_f32 v[8:11], v48, v32, v[8:11]
	v_mfma_f32_16x16x4_f32 v[8:11], v49, v33, v[8:11]
	v_mfma_f32_16x16x4_f32 v[8:11], v50, v34, v[8:11]
	v_mfma_f32_16x16x4_f32 v[8:11], v51, v35, v[8:11]
	v_mfma_f32_16x16x4_f32 v[8:11], v52, v36, v[8:11]
	v_mfma_f32_16x16x4_f32 v[8:11], v53, v37, v[8:11]
	v_mfma_f32_16x16x4_f32 v[8:11], v54, v38, v[8:11]
	v_mfma_f32_16x16x4_f32 v[8:11], v55, v39, v[8:11]
	global_load_dwordx4 v[24:27], v[4:5], off offset:1152
	ds_read_b128 v[32:35], v132 offset:16384
	ds_read_b128 v[36:39], v132 offset:16400
	s_waitcnt vmcnt(3)
	v_lshlrev_b32_e32 v48, 16, v28
	v_and_b32_e32 v49, 0xffff0000, v28
	v_lshlrev_b32_e32 v50, 16, v29
	v_and_b32_e32 v51, 0xffff0000, v29
	v_lshlrev_b32_e32 v52, 16, v30
	v_and_b32_e32 v53, 0xffff0000, v30
	v_lshlrev_b32_e32 v54, 16, v31
	v_and_b32_e32 v55, 0xffff0000, v31
	s_waitcnt lgkmcnt(2)
; #define SHX(v, m) shx_((v), (m), lane)
; __device__ void ba_item(const Params& p, int L, int rp) {
;     ...
;       _Pragma("unroll") for (int j = 0; j < 8; ++j) {
;         float s = 0.f;
;         _Pragma("unroll") for (int e4 = 0; e4 < 4; ++e4) _Pragma("unroll") for (int e = 0; e < 4; ++e) s += hf[e4 * 4 + e] * wr_[j][e4][e];
;         _Pragma("unroll") for (int o = 32; o >= 1; o >>= 1) s += SHX(s, o);
	v_mfma_f32_16x16x4_f32 v[8:11], v48, v40, v[8:11]
	v_mfma_f32_16x16x4_f32 v[8:11], v49, v41, v[8:11]
	v_mfma_f32_16x16x4_f32 v[8:11], v50, v42, v[8:11]
	v_mfma_f32_16x16x4_f32 v[8:11], v51, v43, v[8:11]
	v_mfma_f32_16x16x4_f32 v[8:11], v52, v44, v[8:11]
	v_mfma_f32_16x16x4_f32 v[8:11], v53, v45, v[8:11]
	v_mfma_f32_16x16x4_f32 v[8:11], v54, v46, v[8:11]
	v_mfma_f32_16x16x4_f32 v[8:11], v55, v47, v[8:11]
	global_load_dwordx4 v[28:31], v[4:5], off offset:1216
	ds_read_b128 v[40:43], v132 offset:17408
	ds_read_b128 v[44:47], v132 offset:17424
	s_waitcnt vmcnt(3)
	v_lshlrev_b32_e32 v48, 16, v16
	v_and_b32_e32 v49, 0xffff0000, v16
	v_lshlrev_b32_e32 v50, 16, v17
	v_and_b32_e32 v51, 0xffff0000, v17
	v_lshlrev_b32_e32 v52, 16, v18
	v_and_b32_e32 v53, 0xffff0000, v18
	v_lshlrev_b32_e32 v54, 16, v19
	v_and_b32_e32 v55, 0xffff0000, v19
	s_waitcnt lgkmcnt(2)
	v_mfma_f32_16x16x4_f32 v[8:11], v48, v32, v[8:11]
	v_mfma_f32_16x16x4_f32 v[8:11], v49, v33, v[8:11]
	v_mfma_f32_16x16x4_f32 v[8:11], v50, v34, v[8:11]
	v_mfma_f32_16x16x4_f32 v[8:11], v51, v35, v[8:11]
	v_mfma_f32_16x16x4_f32 v[8:11], v52, v36, v[8:11]
	v_mfma_f32_16x16x4_f32 v[8:11], v53, v37, v[8:11]
	v_mfma_f32_16x16x4_f32 v[8:11], v54, v38, v[8:11]
	v_mfma_f32_16x16x4_f32 v[8:11], v55, v39, v[8:11]
	global_load_dwordx4 v[16:19], v[4:5], off offset:1280
	ds_read_b128 v[32:35], v132 offset:18432
	ds_read_b128 v[36:39], v132 offset:18448
	s_waitcnt vmcnt(3)
	v_lshlrev_b32_e32 v48, 16, v20
	v_and_b32_e32 v49, 0xffff0000, v20
	v_lshlrev_b32_e32 v50, 16, v21
	v_and_b32_e32 v51, 0xffff0000, v21
	v_lshlrev_b32_e32 v52, 16, v22
	v_and_b32_e32 v53, 0xffff0000, v22
	v_lshlrev_b32_e32 v54, 16, v23
	v_and_b32_e32 v55, 0xffff0000, v23
	s_waitcnt lgkmcnt(2)
	v_mfma_f32_16x16x4_f32 v[8:11], v48, v40, v[8:11]
	v_mfma_f32_16x16x4_f32 v[8:11], v49, v41, v[8:11]
	v_mfma_f32_16x16x4_f32 v[8:11], v50, v42, v[8:11]
	v_mfma_f32_16x16x4_f32 v[8:11], v51, v43, v[8:11]
	v_mfma_f32_16x16x4_f32 v[8:11], v52, v44, v[8:11]
	v_mfma_f32_16x16x4_f32 v[8:11], v53, v45, v[8:11]
	v_mfma_f32_16x16x4_f32 v[8:11], v54, v46, v[8:11]
	v_mfma_f32_16x16x4_f32 v[8:11], v55, v47, v[8:11]
	global_load_dwordx4 v[20:23], v[4:5], off offset:1344
	ds_read_b128 v[40:43], v132 offset:19456
	ds_read_b128 v[44:47], v132 offset:19472
	s_waitcnt vmcnt(3)
	v_lshlrev_b32_e32 v48, 16, v24
	v_and_b32_e32 v49, 0xffff0000, v24
	v_lshlrev_b32_e32 v50, 16, v25
	v_and_b32_e32 v51, 0xffff0000, v25
	v_lshlrev_b32_e32 v52, 16, v26
	v_and_b32_e32 v53, 0xffff0000, v26
	v_lshlrev_b32_e32 v54, 16, v27
	v_and_b32_e32 v55, 0xffff0000, v27
	s_waitcnt lgkmcnt(2)
	v_mfma_f32_16x16x4_f32 v[8:11], v48, v32, v[8:11]
	v_mfma_f32_16x16x4_f32 v[8:11], v49, v33, v[8:11]
	v_mfma_f32_16x16x4_f32 v[8:11], v50, v34, v[8:11]
	v_mfma_f32_16x16x4_f32 v[8:11], v51, v35, v[8:11]
	v_mfma_f32_16x16x4_f32 v[8:11], v52, v36, v[8:11]
	v_mfma_f32_16x16x4_f32 v[8:11], v53, v37, v[8:11]
	v_mfma_f32_16x16x4_f32 v[8:11], v54, v38, v[8:11]
	v_mfma_f32_16x16x4_f32 v[8:11], v55, v39, v[8:11]
	global_load_dwordx4 v[24:27], v[4:5], off offset:1408
	ds_read_b128 v[32:35], v132 offset:20480
	ds_read_b128 v[36:39], v132 offset:20496
	s_waitcnt vmcnt(3)
	v_lshlrev_b32_e32 v48, 16, v28
	v_and_b32_e32 v49, 0xffff0000, v28
	v_lshlrev_b32_e32 v50, 16, v29
	v_and_b32_e32 v51, 0xffff0000, v29
	v_lshlrev_b32_e32 v52, 16, v30
	v_and_b32_e32 v53, 0xffff0000, v30
	v_lshlrev_b32_e32 v54, 16, v31
	v_and_b32_e32 v55, 0xffff0000, v31
	s_waitcnt lgkmcnt(2)
	v_mfma_f32_16x16x4_f32 v[8:11], v48, v40, v[8:11]
	v_mfma_f32_16x16x4_f32 v[8:11], v49, v41, v[8:11]
	v_mfma_f32_16x16x4_f32 v[8:11], v50, v42, v[8:11]
	v_mfma_f32_16x16x4_f32 v[8:11], v51, v43, v[8:11]
	v_mfma_f32_16x16x4_f32 v[8:11], v52, v44, v[8:11]
	v_mfma_f32_16x16x4_f32 v[8:11], v53, v45, v[8:11]
	v_mfma_f32_16x16x4_f32 v[8:11], v54, v46, v[8:11]
	v_mfma_f32_16x16x4_f32 v[8:11], v55, v47, v[8:11]
	global_load_dwordx4 v[28:31], v[4:5], off offset:1472
	ds_read_b128 v[40:43], v132 offset:21504
	ds_read_b128 v[44:47], v132 offset:21520
	s_waitcnt vmcnt(3)
	v_lshlrev_b32_e32 v48, 16, v16
	v_and_b32_e32 v49, 0xffff0000, v16
	v_lshlrev_b32_e32 v50, 16, v17
	v_and_b32_e32 v51, 0xffff0000, v17
	v_lshlrev_b32_e32 v52, 16, v18
	v_and_b32_e32 v53, 0xffff0000, v18
	v_lshlrev_b32_e32 v54, 16, v19
	v_and_b32_e32 v55, 0xffff0000, v19
	s_waitcnt lgkmcnt(2)
	v_mfma_f32_16x16x4_f32 v[8:11], v48, v32, v[8:11]
	v_mfma_f32_16x16x4_f32 v[8:11], v49, v33, v[8:11]
	v_mfma_f32_16x16x4_f32 v[8:11], v50, v34, v[8:11]
	v_mfma_f32_16x16x4_f32 v[8:11], v51, v35, v[8:11]
	v_mfma_f32_16x16x4_f32 v[8:11], v52, v36, v[8:11]
	v_mfma_f32_16x16x4_f32 v[8:11], v53, v37, v[8:11]
	v_mfma_f32_16x16x4_f32 v[8:11], v54, v38, v[8:11]
	v_mfma_f32_16x16x4_f32 v[8:11], v55, v39, v[8:11]
	global_load_dwordx4 v[16:19], v[4:5], off offset:1536
	ds_read_b128 v[32:35], v132 offset:22528
	ds_read_b128 v[36:39], v132 offset:22544
	s_waitcnt vmcnt(3)
	v_lshlrev_b32_e32 v48, 16, v20
	v_and_b32_e32 v49, 0xffff0000, v20
	v_lshlrev_b32_e32 v50, 16, v21
	v_and_b32_e32 v51, 0xffff0000, v21
	v_lshlrev_b32_e32 v52, 16, v22
	v_and_b32_e32 v53, 0xffff0000, v22
	v_lshlrev_b32_e32 v54, 16, v23
	v_and_b32_e32 v55, 0xffff0000, v23
	s_waitcnt lgkmcnt(2)
	v_mfma_f32_16x16x4_f32 v[8:11], v48, v40, v[8:11]
	v_mfma_f32_16x16x4_f32 v[8:11], v49, v41, v[8:11]
	v_mfma_f32_16x16x4_f32 v[8:11], v50, v42, v[8:11]
	v_mfma_f32_16x16x4_f32 v[8:11], v51, v43, v[8:11]
	v_mfma_f32_16x16x4_f32 v[8:11], v52, v44, v[8:11]
	v_mfma_f32_16x16x4_f32 v[8:11], v53, v45, v[8:11]
	v_mfma_f32_16x16x4_f32 v[8:11], v54, v46, v[8:11]
	v_mfma_f32_16x16x4_f32 v[8:11], v55, v47, v[8:11]
	global_load_dwordx4 v[20:23], v[4:5], off offset:1600
	ds_read_b128 v[40:43], v132 offset:23552
	ds_read_b128 v[44:47], v132 offset:23568
	s_waitcnt vmcnt(3)
; #define SHX(v, m) shx_((v), (m), lane)
; __device__ void ba_item(const Params& p, int L, int rp) {
;     ...
;       _Pragma("unroll") for (int j = 0; j < 8; ++j) {
;         float s = 0.f;
;         _Pragma("unroll") for (int e4 = 0; e4 < 4; ++e4) _Pragma("unroll") for (int e = 0; e < 4; ++e) s += hf[e4 * 4 + e] * wr_[j][e4][e];
;         _Pragma("unroll") for (int o = 32; o >= 1; o >>= 1) s += SHX(s, o);
	v_lshlrev_b32_e32 v48, 16, v24
	v_and_b32_e32 v49, 0xffff0000, v24
	v_lshlrev_b32_e32 v50, 16, v25
	v_and_b32_e32 v51, 0xffff0000, v25
	v_lshlrev_b32_e32 v52, 16, v26
	v_and_b32_e32 v53, 0xffff0000, v26
	v_lshlrev_b32_e32 v54, 16, v27
	v_and_b32_e32 v55, 0xffff0000, v27
	s_waitcnt lgkmcnt(2)
	v_mfma_f32_16x16x4_f32 v[8:11], v48, v32, v[8:11]
	v_mfma_f32_16x16x4_f32 v[8:11], v49, v33, v[8:11]
	v_mfma_f32_16x16x4_f32 v[8:11], v50, v34, v[8:11]
	v_mfma_f32_16x16x4_f32 v[8:11], v51, v35, v[8:11]
	v_mfma_f32_16x16x4_f32 v[8:11], v52, v36, v[8:11]
	v_mfma_f32_16x16x4_f32 v[8:11], v53, v37, v[8:11]
	v_mfma_f32_16x16x4_f32 v[8:11], v54, v38, v[8:11]
	v_mfma_f32_16x16x4_f32 v[8:11], v55, v39, v[8:11]
	global_load_dwordx4 v[24:27], v[4:5], off offset:1664
	ds_read_b128 v[32:35], v132 offset:24576
	ds_read_b128 v[36:39], v132 offset:24592
	s_waitcnt vmcnt(3)
	v_lshlrev_b32_e32 v48, 16, v28
	v_and_b32_e32 v49, 0xffff0000, v28
	v_lshlrev_b32_e32 v50, 16, v29
	v_and_b32_e32 v51, 0xffff0000, v29
	v_lshlrev_b32_e32 v52, 16, v30
	v_and_b32_e32 v53, 0xffff0000, v30
	v_lshlrev_b32_e32 v54, 16, v31
	v_and_b32_e32 v55, 0xffff0000, v31
	s_waitcnt lgkmcnt(2)
	v_mfma_f32_16x16x4_f32 v[8:11], v48, v40, v[8:11]
	v_mfma_f32_16x16x4_f32 v[8:11], v49, v41, v[8:11]
	v_mfma_f32_16x16x4_f32 v[8:11], v50, v42, v[8:11]
	v_mfma_f32_16x16x4_f32 v[8:11], v51, v43, v[8:11]
	v_mfma_f32_16x16x4_f32 v[8:11], v52, v44, v[8:11]
	v_mfma_f32_16x16x4_f32 v[8:11], v53, v45, v[8:11]
	v_mfma_f32_16x16x4_f32 v[8:11], v54, v46, v[8:11]
	v_mfma_f32_16x16x4_f32 v[8:11], v55, v47, v[8:11]
	global_load_dwordx4 v[28:31], v[4:5], off offset:1728
	ds_read_b128 v[40:43], v132 offset:25600
	ds_read_b128 v[44:47], v132 offset:25616
	s_waitcnt vmcnt(3)
	v_lshlrev_b32_e32 v48, 16, v16
	v_and_b32_e32 v49, 0xffff0000, v16
	v_lshlrev_b32_e32 v50, 16, v17
	v_and_b32_e32 v51, 0xffff0000, v17
	v_lshlrev_b32_e32 v52, 16, v18
	v_and_b32_e32 v53, 0xffff0000, v18
	v_lshlrev_b32_e32 v54, 16, v19
	v_and_b32_e32 v55, 0xffff0000, v19
	s_waitcnt lgkmcnt(2)
	v_mfma_f32_16x16x4_f32 v[8:11], v48, v32, v[8:11]
	v_mfma_f32_16x16x4_f32 v[8:11], v49, v33, v[8:11]
	v_mfma_f32_16x16x4_f32 v[8:11], v50, v34, v[8:11]
	v_mfma_f32_16x16x4_f32 v[8:11], v51, v35, v[8:11]
	v_mfma_f32_16x16x4_f32 v[8:11], v52, v36, v[8:11]
	v_mfma_f32_16x16x4_f32 v[8:11], v53, v37, v[8:11]
	v_mfma_f32_16x16x4_f32 v[8:11], v54, v38, v[8:11]
	v_mfma_f32_16x16x4_f32 v[8:11], v55, v39, v[8:11]
	global_load_dwordx4 v[16:19], v[4:5], off offset:1792
	ds_read_b128 v[32:35], v132 offset:26624
	ds_read_b128 v[36:39], v132 offset:26640
	s_waitcnt vmcnt(3)
	v_lshlrev_b32_e32 v48, 16, v20
	v_and_b32_e32 v49, 0xffff0000, v20
	v_lshlrev_b32_e32 v50, 16, v21
	v_and_b32_e32 v51, 0xffff0000, v21
	v_lshlrev_b32_e32 v52, 16, v22
	v_and_b32_e32 v53, 0xffff0000, v22
	v_lshlrev_b32_e32 v54, 16, v23
	v_and_b32_e32 v55, 0xffff0000, v23
	s_waitcnt lgkmcnt(2)
	v_mfma_f32_16x16x4_f32 v[8:11], v48, v40, v[8:11]
	v_mfma_f32_16x16x4_f32 v[8:11], v49, v41, v[8:11]
	v_mfma_f32_16x16x4_f32 v[8:11], v50, v42, v[8:11]
	v_mfma_f32_16x16x4_f32 v[8:11], v51, v43, v[8:11]
	v_mfma_f32_16x16x4_f32 v[8:11], v52, v44, v[8:11]
	v_mfma_f32_16x16x4_f32 v[8:11], v53, v45, v[8:11]
	v_mfma_f32_16x16x4_f32 v[8:11], v54, v46, v[8:11]
	v_mfma_f32_16x16x4_f32 v[8:11], v55, v47, v[8:11]
	global_load_dwordx4 v[20:23], v[4:5], off offset:1856
	ds_read_b128 v[40:43], v132 offset:27648
	ds_read_b128 v[44:47], v132 offset:27664
	s_waitcnt vmcnt(3)
	v_lshlrev_b32_e32 v48, 16, v24
	v_and_b32_e32 v49, 0xffff0000, v24
	v_lshlrev_b32_e32 v50, 16, v25
	v_and_b32_e32 v51, 0xffff0000, v25
	v_lshlrev_b32_e32 v52, 16, v26
	v_and_b32_e32 v53, 0xffff0000, v26
	v_lshlrev_b32_e32 v54, 16, v27
	v_and_b32_e32 v55, 0xffff0000, v27
	s_waitcnt lgkmcnt(2)
	v_mfma_f32_16x16x4_f32 v[8:11], v48, v32, v[8:11]
	v_mfma_f32_16x16x4_f32 v[8:11], v49, v33, v[8:11]
	v_mfma_f32_16x16x4_f32 v[8:11], v50, v34, v[8:11]
	v_mfma_f32_16x16x4_f32 v[8:11], v51, v35, v[8:11]
	v_mfma_f32_16x16x4_f32 v[8:11], v52, v36, v[8:11]
	v_mfma_f32_16x16x4_f32 v[8:11], v53, v37, v[8:11]
	v_mfma_f32_16x16x4_f32 v[8:11], v54, v38, v[8:11]
	v_mfma_f32_16x16x4_f32 v[8:11], v55, v39, v[8:11]
	global_load_dwordx4 v[24:27], v[4:5], off offset:1920
	ds_read_b128 v[32:35], v132 offset:28672
	ds_read_b128 v[36:39], v132 offset:28688
	s_waitcnt vmcnt(3)
	v_lshlrev_b32_e32 v48, 16, v28
	v_and_b32_e32 v49, 0xffff0000, v28
	v_lshlrev_b32_e32 v50, 16, v29
	v_and_b32_e32 v51, 0xffff0000, v29
	v_lshlrev_b32_e32 v52, 16, v30
	v_and_b32_e32 v53, 0xffff0000, v30
	v_lshlrev_b32_e32 v54, 16, v31
	v_and_b32_e32 v55, 0xffff0000, v31
	s_waitcnt lgkmcnt(2)
	v_mfma_f32_16x16x4_f32 v[8:11], v48, v40, v[8:11]
	v_mfma_f32_16x16x4_f32 v[8:11], v49, v41, v[8:11]
	v_mfma_f32_16x16x4_f32 v[8:11], v50, v42, v[8:11]
	v_mfma_f32_16x16x4_f32 v[8:11], v51, v43, v[8:11]
	v_mfma_f32_16x16x4_f32 v[8:11], v52, v44, v[8:11]
	v_mfma_f32_16x16x4_f32 v[8:11], v53, v45, v[8:11]
	v_mfma_f32_16x16x4_f32 v[8:11], v54, v46, v[8:11]
	v_mfma_f32_16x16x4_f32 v[8:11], v55, v47, v[8:11]
	global_load_dwordx4 v[28:31], v[4:5], off offset:1984
	ds_read_b128 v[40:43], v132 offset:29696
	ds_read_b128 v[44:47], v132 offset:29712
	s_waitcnt vmcnt(3)
	v_lshlrev_b32_e32 v48, 16, v16
	v_and_b32_e32 v49, 0xffff0000, v16
	v_lshlrev_b32_e32 v50, 16, v17
	v_and_b32_e32 v51, 0xffff0000, v17
	v_lshlrev_b32_e32 v52, 16, v18
	v_and_b32_e32 v53, 0xffff0000, v18
	v_lshlrev_b32_e32 v54, 16, v19
	v_and_b32_e32 v55, 0xffff0000, v19
	s_waitcnt lgkmcnt(2)
; #define SHX(v, m) shx_((v), (m), lane)
; __device__ void ba_item(const Params& p, int L, int rp) {
;     ...
;       _Pragma("unroll") for (int j = 0; j < 8; ++j) {
;         float s = 0.f;
;         _Pragma("unroll") for (int e4 = 0; e4 < 4; ++e4) _Pragma("unroll") for (int e = 0; e < 4; ++e) s += hf[e4 * 4 + e] * wr_[j][e4][e];
;         _Pragma("unroll") for (int o = 32; o >= 1; o >>= 1) s += SHX(s, o);
	v_mfma_f32_16x16x4_f32 v[8:11], v48, v32, v[8:11]
	v_mfma_f32_16x16x4_f32 v[8:11], v49, v33, v[8:11]
	v_mfma_f32_16x16x4_f32 v[8:11], v50, v34, v[8:11]
	v_mfma_f32_16x16x4_f32 v[8:11], v51, v35, v[8:11]
	v_mfma_f32_16x16x4_f32 v[8:11], v52, v36, v[8:11]
	v_mfma_f32_16x16x4_f32 v[8:11], v53, v37, v[8:11]
	v_mfma_f32_16x16x4_f32 v[8:11], v54, v38, v[8:11]
	v_mfma_f32_16x16x4_f32 v[8:11], v55, v39, v[8:11]
	ds_read_b128 v[32:35], v132 offset:30720
	ds_read_b128 v[36:39], v132 offset:30736
	s_waitcnt vmcnt(2)
	v_lshlrev_b32_e32 v48, 16, v20
	v_and_b32_e32 v49, 0xffff0000, v20
	v_lshlrev_b32_e32 v50, 16, v21
	v_and_b32_e32 v51, 0xffff0000, v21
	v_lshlrev_b32_e32 v52, 16, v22
	v_and_b32_e32 v53, 0xffff0000, v22
	v_lshlrev_b32_e32 v54, 16, v23
	v_and_b32_e32 v55, 0xffff0000, v23
	s_waitcnt lgkmcnt(2)
	v_mfma_f32_16x16x4_f32 v[8:11], v48, v40, v[8:11]
	v_mfma_f32_16x16x4_f32 v[8:11], v49, v41, v[8:11]
	v_mfma_f32_16x16x4_f32 v[8:11], v50, v42, v[8:11]
	v_mfma_f32_16x16x4_f32 v[8:11], v51, v43, v[8:11]
	v_mfma_f32_16x16x4_f32 v[8:11], v52, v44, v[8:11]
	v_mfma_f32_16x16x4_f32 v[8:11], v53, v45, v[8:11]
	v_mfma_f32_16x16x4_f32 v[8:11], v54, v46, v[8:11]
	v_mfma_f32_16x16x4_f32 v[8:11], v55, v47, v[8:11]
	ds_read_b128 v[40:43], v132 offset:31744
	ds_read_b128 v[44:47], v132 offset:31760
	s_waitcnt vmcnt(1)
	v_lshlrev_b32_e32 v48, 16, v24
	v_and_b32_e32 v49, 0xffff0000, v24
	v_lshlrev_b32_e32 v50, 16, v25
	v_and_b32_e32 v51, 0xffff0000, v25
	v_lshlrev_b32_e32 v52, 16, v26
	v_and_b32_e32 v53, 0xffff0000, v26
	v_lshlrev_b32_e32 v54, 16, v27
	v_and_b32_e32 v55, 0xffff0000, v27
	s_waitcnt lgkmcnt(2)
	v_mfma_f32_16x16x4_f32 v[8:11], v48, v32, v[8:11]
	v_mfma_f32_16x16x4_f32 v[8:11], v49, v33, v[8:11]
	v_mfma_f32_16x16x4_f32 v[8:11], v50, v34, v[8:11]
	v_mfma_f32_16x16x4_f32 v[8:11], v51, v35, v[8:11]
	v_mfma_f32_16x16x4_f32 v[8:11], v52, v36, v[8:11]
	v_mfma_f32_16x16x4_f32 v[8:11], v53, v37, v[8:11]
	v_mfma_f32_16x16x4_f32 v[8:11], v54, v38, v[8:11]
	v_mfma_f32_16x16x4_f32 v[8:11], v55, v39, v[8:11]
	s_waitcnt vmcnt(0)
	v_lshlrev_b32_e32 v48, 16, v28
	v_and_b32_e32 v49, 0xffff0000, v28
	v_lshlrev_b32_e32 v50, 16, v29
	v_and_b32_e32 v51, 0xffff0000, v29
	v_lshlrev_b32_e32 v52, 16, v30
	v_and_b32_e32 v53, 0xffff0000, v30
	v_lshlrev_b32_e32 v54, 16, v31
	v_and_b32_e32 v55, 0xffff0000, v31
	s_waitcnt lgkmcnt(0)
; __device__ __forceinline__ float fexp(float x) { return __builtin_amdgcn_exp2f(x * 1.4426950408889634f); }
; __device__ __forceinline__ float flog(float x) { return __builtin_amdgcn_logf(x) * 0.6931471805599453f; }
; __device__ __forceinline__ float frsq(float x) { return __builtin_amdgcn_rsqf(x); }
; __device__ __forceinline__ float sigmoidf_(float x) { return frcp(1.0f + fexp(-x)); }
; #define SHX(v, m) shx_((v), (m), lane)
; __device__ void ba_item(const Params& p, int L, int rp) {
;     ...
;       _Pragma("unroll") for (int j = 0; j < 8; ++j) {
;         float s = 0.f;
;         _Pragma("unroll") for (int e4 = 0; e4 < 4; ++e4) _Pragma("unroll") for (int e = 0; e < 4; ++e) s += hf[e4 * 4 + e] * wr_[j][e4][e];
;         _Pragma("unroll") for (int o = 32; o >= 1; o >>= 1) s += SHX(s, o);
;         a[j] = s;
;       }
;       if (lane < 8) {
;         float s16 = 0.f;
;         _Pragma("unroll") for (int i = 0; i < 4; ++i) s16 += (ps[u][i][0] + ps[u][i][1]) + (ps[u][i][2] + ps[u][i][3]);
;         float rs = frsq(s16 * (1.0f / 1024.0f) + 1e-6f);
;         float v = 0.f;
;         _Pragma("unroll") for (int j = 0; j < 8; ++j) if (lane == j) v = a[j];
;         v *= rs;
;         float r;
;         if (lane < 4) r = sigmoidf_(v);
;         else {
;           int hh = lane - 4;
;           float z = v + p.dn_dt_bias[(L >> 1) * 4 + hh];
;           float sp = (z > 20.f) ? z : flog(1.0f + fexp(z));
;           r = -fexp(p.dn_a_log[(L >> 1) * 4 + hh]) * sp;
;         }
;         miscw[MF_BG + (long)row * 8 + lane] = r;
;       }
	v_mfma_f32_16x16x4_f32 v[8:11], v48, v40, v[8:11]
	v_mfma_f32_16x16x4_f32 v[8:11], v49, v41, v[8:11]
	v_mfma_f32_16x16x4_f32 v[8:11], v50, v42, v[8:11]
	v_mfma_f32_16x16x4_f32 v[8:11], v51, v43, v[8:11]
	v_mfma_f32_16x16x4_f32 v[8:11], v52, v44, v[8:11]
	v_mfma_f32_16x16x4_f32 v[8:11], v53, v45, v[8:11]
	v_mfma_f32_16x16x4_f32 v[8:11], v54, v46, v[8:11]
	v_mfma_f32_16x16x4_f32 v[8:11], v55, v47, v[8:11]
	v_cmp_gt_u32_e32 vcc, 8, v2
	s_and_saveexec_b64 s[12:13], vcc
	s_nop 4
	v_add_f32_e32 v56, v56, v57
	v_add_f32_e32 v58, v58, v59
	v_add_f32_e32 v56, v56, v58
	v_add_f32_e32 v60, v60, v61
	v_add_f32_e32 v62, v62, v63
	v_add_f32_e32 v60, v60, v62
	v_add_f32_e32 v64, v64, v65
	v_add_f32_e32 v66, v66, v67
	v_add_f32_e32 v64, v64, v66
	v_add_f32_e32 v68, v68, v69
	v_add_f32_e32 v70, v70, v71
	v_add_f32_e32 v68, v68, v70
	v_add_f32_e32 v56, 0, v56
	v_add_f32_e32 v56, v60, v56
	v_add_f32_e32 v56, v64, v56
	v_add_f32_e32 v56, v68, v56
	v_fmamk_f32 v56, v56, 0x3a800000, v201
	v_rsq_f32_e32 v56, v56
	s_nop 0
	v_mul_f32_e32 v128, v8, v56
	v_mul_f32_e32 v129, 0xbfb8aa3b, v128
	v_exp_f32_e32 v129, v129
	s_nop 0
	v_add_f32_e32 v129, 1.0, v129
	v_rcp_f32_e32 v129, v129
	v_add_f32_e32 v130, v128, v126
	v_mul_f32_e32 v131, 0x3fb8aa3b, v130
	v_exp_f32_e32 v131, v131
	v_cmp_lt_f32_e64 s[0:1], s57, v130
	v_add_f32_e32 v131, 1.0, v131
	v_log_f32_e32 v131, v131
	s_nop 0
	v_mul_f32_e32 v131, 0x3f317218, v131
	v_cndmask_b32_e64 v130, v131, v130, s[0:1]
	v_mul_f32_e32 v131, 0x3fb8aa3b, v127
	v_exp_f32_e32 v131, v131
	s_nop 0
	v_mul_f32_e64 v130, v130, -v131
	v_cmp_gt_u32_e64 s[0:1], 4, v122
	s_nop 1
	v_cndmask_b32_e64 v130, v130, v129, s[0:1]
	global_store_dword v[124:125], v130, off offset:0
	v_add_f32_e32 v72, v72, v73
	v_add_f32_e32 v74, v74, v75
	v_add_f32_e32 v72, v72, v74
	v_add_f32_e32 v76, v76, v77
	v_add_f32_e32 v78, v78, v79
	v_add_f32_e32 v76, v76, v78
	v_add_f32_e32 v80, v80, v81
	v_add_f32_e32 v82, v82, v83
	v_add_f32_e32 v80, v80, v82
	v_add_f32_e32 v84, v84, v85
	v_add_f32_e32 v86, v86, v87
	v_add_f32_e32 v84, v84, v86
	v_add_f32_e32 v72, 0, v72
	v_add_f32_e32 v72, v76, v72
	v_add_f32_e32 v72, v80, v72
	v_add_f32_e32 v72, v84, v72
	v_fmamk_f32 v72, v72, 0x3a800000, v201
	v_rsq_f32_e32 v72, v72
	s_nop 0
	v_mul_f32_e32 v128, v9, v72
	v_mul_f32_e32 v129, 0xbfb8aa3b, v128
	v_exp_f32_e32 v129, v129
	s_nop 0
	v_add_f32_e32 v129, 1.0, v129
	v_rcp_f32_e32 v129, v129
	v_add_f32_e32 v130, v128, v126
	v_mul_f32_e32 v131, 0x3fb8aa3b, v130
	v_exp_f32_e32 v131, v131
	v_cmp_lt_f32_e64 s[0:1], s57, v130
	v_add_f32_e32 v131, 1.0, v131
	v_log_f32_e32 v131, v131
	s_nop 0
	v_mul_f32_e32 v131, 0x3f317218, v131
	v_cndmask_b32_e64 v130, v131, v130, s[0:1]
	v_mul_f32_e32 v131, 0x3fb8aa3b, v127
	v_exp_f32_e32 v131, v131
	s_nop 0
	v_mul_f32_e64 v130, v130, -v131
	v_cmp_gt_u32_e64 s[0:1], 4, v122
	s_nop 1
	v_cndmask_b32_e64 v130, v130, v129, s[0:1]
	global_store_dword v[124:125], v130, off offset:32
	v_add_f32_e32 v88, v88, v89
	v_add_f32_e32 v90, v90, v91
	v_add_f32_e32 v88, v88, v90
	v_add_f32_e32 v92, v92, v93
	v_add_f32_e32 v94, v94, v95
	v_add_f32_e32 v92, v92, v94
	v_add_f32_e32 v96, v96, v97
	v_add_f32_e32 v98, v98, v99
	v_add_f32_e32 v96, v96, v98
	v_add_f32_e32 v100, v100, v101
	v_add_f32_e32 v102, v102, v103
	v_add_f32_e32 v100, v100, v102
	v_add_f32_e32 v88, 0, v88
	v_add_f32_e32 v88, v92, v88
	v_add_f32_e32 v88, v96, v88
	v_add_f32_e32 v88, v100, v88
	v_fmamk_f32 v88, v88, 0x3a800000, v201
	v_rsq_f32_e32 v88, v88
	s_nop 0
	v_mul_f32_e32 v128, v10, v88
	v_mul_f32_e32 v129, 0xbfb8aa3b, v128
	v_exp_f32_e32 v129, v129
	s_nop 0
	v_add_f32_e32 v129, 1.0, v129
	v_rcp_f32_e32 v129, v129
	v_add_f32_e32 v130, v128, v126
	v_mul_f32_e32 v131, 0x3fb8aa3b, v130
	v_exp_f32_e32 v131, v131
	v_cmp_lt_f32_e64 s[0:1], s57, v130
	v_add_f32_e32 v131, 1.0, v131
	v_log_f32_e32 v131, v131
	s_nop 0
	v_mul_f32_e32 v131, 0x3f317218, v131
	v_cndmask_b32_e64 v130, v131, v130, s[0:1]
	v_mul_f32_e32 v131, 0x3fb8aa3b, v127
	v_exp_f32_e32 v131, v131
	s_nop 0
	v_mul_f32_e64 v130, v130, -v131
	v_cmp_gt_u32_e64 s[0:1], 4, v122
	s_nop 1
	v_cndmask_b32_e64 v130, v130, v129, s[0:1]
	global_store_dword v[124:125], v130, off offset:64
	v_add_f32_e32 v104, v104, v105
	v_add_f32_e32 v106, v106, v107
	v_add_f32_e32 v104, v104, v106
	v_add_f32_e32 v108, v108, v109
	v_add_f32_e32 v110, v110, v111
	v_add_f32_e32 v108, v108, v110
	v_add_f32_e32 v112, v112, v113
	v_add_f32_e32 v114, v114, v115
	v_add_f32_e32 v112, v112, v114
	v_add_f32_e32 v116, v116, v117
	v_add_f32_e32 v118, v118, v119
	v_add_f32_e32 v116, v116, v118
	v_add_f32_e32 v104, 0, v104
	v_add_f32_e32 v104, v108, v104
	v_add_f32_e32 v104, v112, v104
	v_add_f32_e32 v104, v116, v104
	v_fmamk_f32 v104, v104, 0x3a800000, v201
	v_rsq_f32_e32 v104, v104
	s_nop 0
	v_mul_f32_e32 v128, v11, v104
	v_mul_f32_e32 v129, 0xbfb8aa3b, v128
	v_exp_f32_e32 v129, v129
	s_nop 0
	v_add_f32_e32 v129, 1.0, v129
	v_rcp_f32_e32 v129, v129
	v_add_f32_e32 v130, v128, v126
	v_mul_f32_e32 v131, 0x3fb8aa3b, v130
	v_exp_f32_e32 v131, v131
	v_cmp_lt_f32_e64 s[0:1], s57, v130
	v_add_f32_e32 v131, 1.0, v131
	v_log_f32_e32 v131, v131
	s_nop 0
	v_mul_f32_e32 v131, 0x3f317218, v131
	v_cndmask_b32_e64 v130, v131, v130, s[0:1]
	v_mul_f32_e32 v131, 0x3fb8aa3b, v127
	v_exp_f32_e32 v131, v131
	s_nop 0
	v_mul_f32_e64 v130, v130, -v131
	v_cmp_gt_u32_e64 s[0:1], 4, v122
	s_nop 1
	v_cndmask_b32_e64 v130, v130, v129, s[0:1]
	global_store_dword v[124:125], v130, off offset:96
	s_or_b64 exec, exec, s[12:13]
	s_barrier
	s_branch .LBB0_627
